# MH: selected-branch loop reads the tile's selection mask word before the iteration barrier instead of after it
# baseline (speedup 1.0000x reference)
.LBB0_909:
	s_lshr_b32 s1, s16, 3
	s_and_b32 s1, s1, 0x1ffffffc
	v_add_u32_e32 v50, s1, v114
	ds_read_b32 v50, v50
	s_cmp_gt_i32 s15, s14
	s_waitcnt lgkmcnt(0)
	s_barrier
	s_cbranch_scc1 .Ld5s_inactive
	s_and_b32 s1, s16, 31
	v_bfe_u32 v51, v50, s1, 1
	v_cmp_ne_u32_e32 vcc, 0, v51
	s_cbranch_vccz .Ld5s_inactive
	s_mul_i32 s22, s0, 0x4a00
	v_add3_u32 v193, s22, v182, v130
	v_lshrrev_b32_e32 v147, s1, v50
	ds_read_b128 v[148:151], v193 offset:4608
	ds_read_b128 v[50:53], v193
	ds_read_b128 v[152:155], v193 offset:32
	ds_read_b128 v[236:239], v193 offset:4640
	ds_read_b128 v[240:243], v193 offset:64
	ds_read_b128 v[244:247], v193 offset:4672
	ds_read_b128 v[248:251], v193 offset:96
	s_add_i32 s23, s15, 63
	v_cmp_le_i32_e32 vcc, s23, v128
	s_waitcnt lgkmcnt(5)
	v_mfma_f32_32x32x16_bf16 v[66:81], v[50:53], v[82:85], v[34:49]
	s_waitcnt lgkmcnt(4)
	v_mfma_f32_32x32x16_bf16 v[66:81], v[152:155], v[86:89], v[66:81]
	ds_read_b128 v[152:155], v193 offset:4704
	v_and_b32_e32 v147, 1, v147
	s_cmp_lg_u64 vcc, exec
	s_mov_b64 s[0:1], -1
	v_cmp_eq_u32_e32 vcc, 1, v147
	s_mov_b64 s[4:5], -1
	v_mfma_f32_32x32x16_bf16 v[50:65], v[148:151], v[82:85], v[34:49]
	s_waitcnt lgkmcnt(4)
	v_mfma_f32_32x32x16_bf16 v[50:65], v[236:239], v[86:89], v[50:65]
	s_waitcnt lgkmcnt(3)
	v_mfma_f32_32x32x16_bf16 v[66:81], v[240:243], v[90:93], v[66:81]
	s_waitcnt lgkmcnt(2)
	v_mfma_f32_32x32x16_bf16 v[50:65], v[244:247], v[90:93], v[50:65]
	s_waitcnt lgkmcnt(1)
	v_mfma_f32_32x32x16_bf16 v[66:81], v[248:251], v[94:97], v[66:81]
	s_waitcnt lgkmcnt(0)
	v_mfma_f32_32x32x16_bf16 v[50:65], v[152:155], v[94:97], v[50:65]
	s_cbranch_scc0 .LBB0_917
	v_cndmask_b32_e32 v148, -1, v128, vcc
	v_cmp_le_i32_e32 vcc, s23, v148
	s_cmp_eq_u64 vcc, exec
	s_cbranch_scc1 .LBB0_916
	v_add_u32_e32 v149, s15, v125
	v_cmp_lt_i32_e32 vcc, v149, v148
	v_add_u32_e32 v150, 2, v149
	s_nop 2
	v_cndmask_b32_e32 v67, v169, v67, vcc
	v_cmp_le_i32_e32 vcc, v149, v148
	s_nop 1
	v_cndmask_b32_e32 v66, v169, v66, vcc
	v_cmp_le_i32_e32 vcc, v150, v148
	v_add_u32_e32 v150, 3, v149
	s_nop 0
	v_cndmask_b32_e32 v68, v169, v68, vcc
	v_cmp_le_i32_e32 vcc, v150, v148
	v_add_u32_e32 v150, 8, v149
	s_nop 0
	v_cndmask_b32_e32 v69, v169, v69, vcc
	v_cmp_le_i32_e32 vcc, v150, v148
	v_add_u32_e32 v150, 9, v149
	s_nop 0
	v_cndmask_b32_e32 v70, v169, v70, vcc
	v_cmp_le_i32_e32 vcc, v150, v148
	v_add_u32_e32 v150, 10, v149
	s_nop 0
	v_cndmask_b32_e32 v71, v169, v71, vcc
	v_cmp_le_i32_e32 vcc, v150, v148
	v_add_u32_e32 v150, 11, v149
	s_nop 0
	v_cndmask_b32_e32 v72, v169, v72, vcc
	v_cmp_le_i32_e32 vcc, v150, v148
	v_add_u32_e32 v150, 16, v149
	s_nop 0
	v_cndmask_b32_e32 v73, v169, v73, vcc
	v_cmp_le_i32_e32 vcc, v150, v148
	v_add_u32_e32 v150, 17, v149
	s_nop 0
	v_cndmask_b32_e32 v74, v169, v74, vcc
	v_cmp_le_i32_e32 vcc, v150, v148
	v_add_u32_e32 v150, 18, v149
	s_nop 0
	v_cndmask_b32_e32 v75, v169, v75, vcc
	v_cmp_le_i32_e32 vcc, v150, v148
	v_add_u32_e32 v150, 19, v149
	s_nop 0
	v_cndmask_b32_e32 v76, v169, v76, vcc
	v_cmp_le_i32_e32 vcc, v150, v148
	v_add_u32_e32 v150, 24, v149
	s_nop 0
	v_cndmask_b32_e32 v77, v169, v77, vcc
	v_cmp_le_i32_e32 vcc, v150, v148
	v_add_u32_e32 v150, 25, v149
	s_nop 0
	v_cndmask_b32_e32 v78, v169, v78, vcc
	v_cmp_le_i32_e32 vcc, v150, v148
	v_add_u32_e32 v150, 26, v149
	s_nop 0
	v_cndmask_b32_e32 v79, v169, v79, vcc
	v_cmp_le_i32_e32 vcc, v150, v148
	v_add_u32_e32 v150, 27, v149
	s_nop 0
	v_cndmask_b32_e32 v80, v169, v80, vcc
	v_cmp_le_i32_e32 vcc, v150, v148
	v_add_u32_e32 v150, 32, v149
	s_nop 0
	v_cndmask_b32_e32 v81, v169, v81, vcc
	v_cmp_le_i32_e32 vcc, v150, v148
	v_add_u32_e32 v150, 33, v149
	s_nop 0
	v_cndmask_b32_e32 v50, v169, v50, vcc
	v_cmp_le_i32_e32 vcc, v150, v148
	v_add_u32_e32 v150, 34, v149
	s_nop 0
	v_cndmask_b32_e32 v51, v169, v51, vcc
	v_cmp_le_i32_e32 vcc, v150, v148
	v_add_u32_e32 v150, 35, v149
	s_nop 0
	v_cndmask_b32_e32 v52, v169, v52, vcc
	v_cmp_le_i32_e32 vcc, v150, v148
	v_add_u32_e32 v150, 40, v149
	s_nop 0
	v_cndmask_b32_e32 v53, v169, v53, vcc
	v_cmp_le_i32_e32 vcc, v150, v148
	v_add_u32_e32 v150, 41, v149
	s_nop 0
	v_cndmask_b32_e32 v54, v169, v54, vcc
	v_cmp_le_i32_e32 vcc, v150, v148
	v_add_u32_e32 v150, 42, v149
	s_nop 0
	v_cndmask_b32_e32 v55, v169, v55, vcc
	v_cmp_le_i32_e32 vcc, v150, v148
	v_add_u32_e32 v150, 43, v149
	s_nop 0
	v_cndmask_b32_e32 v56, v169, v56, vcc
	v_cmp_le_i32_e32 vcc, v150, v148
	v_add_u32_e32 v150, 48, v149
	s_nop 0
	v_cndmask_b32_e32 v57, v169, v57, vcc
	v_cmp_le_i32_e32 vcc, v150, v148
	v_add_u32_e32 v150, 49, v149
	s_nop 0
	v_cndmask_b32_e32 v58, v169, v58, vcc
	v_cmp_le_i32_e32 vcc, v150, v148
	v_add_u32_e32 v150, 50, v149
	s_nop 0
	v_cndmask_b32_e32 v59, v169, v59, vcc
	v_cmp_le_i32_e32 vcc, v150, v148
	v_add_u32_e32 v150, 51, v149
	s_nop 0
	v_cndmask_b32_e32 v60, v169, v60, vcc
	v_cmp_le_i32_e32 vcc, v150, v148
	v_add_u32_e32 v150, 56, v149
	s_nop 0
	v_cndmask_b32_e32 v61, v169, v61, vcc
	v_cmp_le_i32_e32 vcc, v150, v148
	v_add_u32_e32 v150, 57, v149
	s_nop 0
	v_cndmask_b32_e32 v62, v169, v62, vcc
	v_cmp_le_i32_e32 vcc, v150, v148
	v_add_u32_e32 v150, 58, v149
	v_add_u32_e32 v149, 59, v149
	v_cndmask_b32_e32 v63, v169, v63, vcc
	v_cmp_le_i32_e32 vcc, v150, v148
	s_nop 1
	v_cndmask_b32_e32 v64, v169, v64, vcc
	v_cmp_gt_i32_e32 vcc, v149, v148
	s_and_saveexec_b64 s[4:5], vcc
	v_mov_b32_e32 v65, 0xf149f2ca
	s_or_b64 exec, exec, s[4:5]
